# out/down/in-proj GEMMs: last unit's final K iteration no longer issues the 14 unused fallback prefetch loads
# baseline (speedup 1.0000x reference)
.LBB0_306:
	v_bfe_u32 v23, v229, 4, 2
	v_lshlrev_b32_e32 v25, 4, v23
	v_lshlrev_b32_e32 v26, 2, v5
	s_and_b32 s49, s6, 3
	v_lshl_or_b32 v25, v5, 6, v25
	s_lshl_b32 s6, s7, 13
	v_and_b32_e32 v26, 32, v26
	v_bitop3_b32 v27, v25, s6, v26 bitop3:0xde
	s_lshl_b32 s6, s49, 12
	s_lshr_b32 s50, s40, 6
	v_lshl_or_b32 v212, s7, 6, v5
	v_bitop3_b32 v213, s6, v25, v26 bitop3:0xf6
	v_readlane_b32 s6, v254, 37
	v_readlane_b32 s7, v254, 38
	s_add_u32 s22, s6, 0x6800000
	s_addc_u32 s23, s7, 0
	s_add_u32 s24, s6, 0x8c00000
	s_addc_u32 s25, s7, 0
	s_add_i32 m0, s45, 0x18000
	v_lshl_add_u64 v[6:7], v[6:7], 0, s[96:97]
	s_waitcnt vmcnt(2)
	s_barrier
	global_load_lds_dwordx4 v[6:7], off
	v_lshl_add_u64 v[6:7], v[8:9], 0, s[96:97]
	s_add_i32 m0, s45, 0x1a000
	s_add_i32 s51, s45, 0x8000
	global_load_lds_dwordx4 v[6:7], off
	v_lshl_add_u64 v[6:7], v[14:15], 0, s[96:97]
	s_mov_b32 m0, s51
	s_add_i32 s52, s45, 0xa000
	global_load_lds_dwordx4 v[6:7], off
	v_lshl_add_u64 v[6:7], v[16:17], 0, s[96:97]
	s_mov_b32 m0, s52
	s_add_i32 s53, s50, -2
	global_load_lds_dwordx4 v[6:7], off
	s_add_i32 m0, s45, 0x1c000
	v_lshl_add_u64 v[6:7], v[10:11], 0, s[96:97]
	global_load_lds_dwordx4 v[6:7], off
	v_lshl_add_u64 v[6:7], v[12:13], 0, s[96:97]
	s_add_i32 m0, s45, 0x1e000
	v_add_u32_e32 v0, v22, v0
	global_load_lds_dwordx4 v[6:7], off
	v_and_b32_e32 v7, 0xffffffc0, v223
	v_xor_b32_e32 v6, 16, v223
	v_add_u32_e32 v7, 64, v7
	v_cmp_lt_i32_e32 vcc, v6, v7
	s_cmpk_lt_u32 s8, 0x100
	v_readlane_b32 s8, v254, 41
	v_cndmask_b32_e32 v6, v223, v6, vcc
	v_lshlrev_b32_e32 v215, 2, v6
	v_xor_b32_e32 v6, 32, v223
	v_add_lshl_u32 v0, v0, v21, 1
	s_waitcnt vmcnt(6)
	s_cselect_b64 s[26:27], -1, 0
	s_ashr_i32 s55, s90, 31
	s_ashr_i32 s57, s8, 31
	v_cmp_lt_i32_e32 vcc, v6, v7
	v_lshl_add_u64 v[206:207], s[18:19], 0, v[0:1]
	v_add_u32_e32 v0, v20, v18
	v_lshlrev_b32_e32 v24, 3, v23
	s_cmp_lg_u64 s[16:17], 0
	v_cndmask_b32_e32 v6, v223, v6, vcc
	v_add_lshl_u32 v0, v0, v19, 1
	v_lshl_or_b32 v214, s49, 5, v24
	s_mov_b32 s54, 0
	v_cmp_eq_u32_e64 s[6:7], 0, v23
	s_cselect_b64 s[28:29], -1, 0
	v_lshlrev_b32_e32 v216, 2, v6
	v_lshl_add_u64 v[208:209], s[18:19], 0, v[0:1]
	v_add_u32_e32 v217, 0, v27
	s_barrier
	s_branch .LBB0_309
.Lmy_g2_s2_last:
	s_waitcnt vmcnt(2)
	s_branch .Lmy_g2_s2_join
.Lmy_g2_s3_last:
	s_waitcnt vmcnt(0)
	s_branch .Lmy_g2_s3_join
.Lmy_g2_s4_last:
	s_waitcnt vmcnt(0)
	s_branch .Lmy_g2_s4_join
.LBB0_307:
	s_mov_b64 s[8:9], 0

.LBB0_319:
	s_cmp_lg_u64 s[8:9], 0
	s_cselect_b32 s99, s50, 0x7fffffff
	s_add_u32 s61, s36, 0x100
	s_addc_u32 s62, s37, 0
	s_add_u32 s10, s38, 0x80
	v_mov_b32_e32 v6, 0
	s_addc_u32 s11, s39, 0
	s_mov_b32 s36, 0
	v_mov_b32_e32 v7, v6
	v_mov_b32_e32 v8, v6
	v_mov_b32_e32 v9, v6
	v_mov_b32_e32 v10, v6
	v_mov_b32_e32 v11, v6
	v_mov_b32_e32 v12, v6
	v_mov_b32_e32 v13, v6
	v_mov_b32_e32 v22, v6
	v_mov_b32_e32 v23, v6
	v_mov_b32_e32 v24, v6
	v_mov_b32_e32 v25, v6
	v_mov_b32_e32 v26, v6
	v_mov_b32_e32 v27, v6
	v_mov_b32_e32 v28, v6
	v_mov_b32_e32 v29, v6
	v_mov_b32_e32 v38, v6
	v_mov_b32_e32 v39, v6
	v_mov_b32_e32 v40, v6
	v_mov_b32_e32 v41, v6
	v_mov_b32_e32 v42, v6
	v_mov_b32_e32 v43, v6
	v_mov_b32_e32 v44, v6
	v_mov_b32_e32 v45, v6
	v_mov_b32_e32 v54, v6
	v_mov_b32_e32 v55, v6
	v_mov_b32_e32 v56, v6
	v_mov_b32_e32 v57, v6
	v_mov_b32_e32 v58, v6
	v_mov_b32_e32 v59, v6
	v_mov_b32_e32 v60, v6
	v_mov_b32_e32 v61, v6
	v_mov_b32_e32 v14, v6
	v_mov_b32_e32 v15, v6
	v_mov_b32_e32 v16, v6
	v_mov_b32_e32 v17, v6
	v_mov_b32_e32 v18, v6
	v_mov_b32_e32 v19, v6
	v_mov_b32_e32 v20, v6
	v_mov_b32_e32 v21, v6
	v_mov_b32_e32 v30, v6
	v_mov_b32_e32 v31, v6
	v_mov_b32_e32 v32, v6
	v_mov_b32_e32 v33, v6
	v_mov_b32_e32 v34, v6
	v_mov_b32_e32 v35, v6
	v_mov_b32_e32 v36, v6
	v_mov_b32_e32 v37, v6
	v_mov_b32_e32 v46, v6
	v_mov_b32_e32 v47, v6
	v_mov_b32_e32 v48, v6
	v_mov_b32_e32 v49, v6
	v_mov_b32_e32 v50, v6
	v_mov_b32_e32 v51, v6
	v_mov_b32_e32 v52, v6
	v_mov_b32_e32 v53, v6
	v_mov_b32_e32 v62, v6
	v_mov_b32_e32 v63, v6
	v_mov_b32_e32 v64, v6
	v_mov_b32_e32 v65, v6
	v_mov_b32_e32 v66, v6
	v_mov_b32_e32 v67, v6
	v_mov_b32_e32 v68, v6
	v_mov_b32_e32 v69, v6
	v_mov_b32_e32 v70, v6
	v_mov_b32_e32 v71, v6
	v_mov_b32_e32 v72, v6
	v_mov_b32_e32 v73, v6
	v_mov_b32_e32 v74, v6
	v_mov_b32_e32 v75, v6
	v_mov_b32_e32 v76, v6
	v_mov_b32_e32 v77, v6
	v_mov_b32_e32 v90, v6
	v_mov_b32_e32 v91, v6
	v_mov_b32_e32 v92, v6
	v_mov_b32_e32 v93, v6
	v_mov_b32_e32 v94, v6
	v_mov_b32_e32 v95, v6
	v_mov_b32_e32 v96, v6
	v_mov_b32_e32 v97, v6
	v_mov_b32_e32 v114, v6
	v_mov_b32_e32 v115, v6
	v_mov_b32_e32 v116, v6
	v_mov_b32_e32 v117, v6
	v_mov_b32_e32 v122, v6
	v_mov_b32_e32 v123, v6
	v_mov_b32_e32 v124, v6
	v_mov_b32_e32 v125, v6
	v_mov_b32_e32 v142, v6
	v_mov_b32_e32 v143, v6
	v_mov_b32_e32 v144, v6
	v_mov_b32_e32 v145, v6
	v_mov_b32_e32 v146, v6
	v_mov_b32_e32 v147, v6
	v_mov_b32_e32 v148, v6
	v_mov_b32_e32 v149, v6
	v_mov_b32_e32 v78, v6
	v_mov_b32_e32 v79, v6
	v_mov_b32_e32 v80, v6
	v_mov_b32_e32 v81, v6
	v_mov_b32_e32 v82, v6
	v_mov_b32_e32 v83, v6
	v_mov_b32_e32 v84, v6
	v_mov_b32_e32 v85, v6
	v_mov_b32_e32 v102, v6
	v_mov_b32_e32 v103, v6
	v_mov_b32_e32 v104, v6
	v_mov_b32_e32 v105, v6
	v_mov_b32_e32 v106, v6
	v_mov_b32_e32 v107, v6
	v_mov_b32_e32 v108, v6
	v_mov_b32_e32 v109, v6
	v_mov_b32_e32 v126, v6
	v_mov_b32_e32 v127, v6
	v_mov_b32_e32 v128, v6
	v_mov_b32_e32 v129, v6
	v_mov_b32_e32 v130, v6
	v_mov_b32_e32 v131, v6
	v_mov_b32_e32 v132, v6
	v_mov_b32_e32 v133, v6
	v_mov_b32_e32 v162, v6
	v_mov_b32_e32 v163, v6
	v_mov_b32_e32 v164, v6
	v_mov_b32_e32 v165, v6
	v_mov_b32_e32 v166, v6
	v_mov_b32_e32 v167, v6
	v_mov_b32_e32 v168, v6
	v_mov_b32_e32 v169, v6
.LBB0_320:
	s_add_i32 s38, s36, 2
	s_add_u32 s39, s10, 0x80
	s_addc_u32 s37, s11, 0
	s_add_i32 s63, 0, 0x10000
	s_cmp_eq_u32 s53, s36
	s_cselect_b32 s37, s31, s37
	s_cselect_b32 s36, s30, s39
	v_add_u32_e32 v0, s63, v213
	s_cselect_b32 s65, s35, s62
	s_cselect_b32 s64, s34, s61
	s_add_i32 s39, 0, 0x14000
	ds_read_b128 v[86:89], v0
	ds_read_b128 v[98:101], v0 offset:1024
	ds_read_b128 v[110:113], v0 offset:2048
	ds_read_b128 v[118:121], v0 offset:3072
	v_add_u32_e32 v0, s39, v213
	ds_read_b128 v[134:137], v0
	ds_read_b128 v[138:141], v0 offset:1024
	ds_read_b128 v[150:153], v0 offset:2048
	ds_read_b128 v[154:157], v0 offset:3072
	v_lshl_add_u64 v[210:211], s[10:11], 0, v[208:209]
	s_add_i32 m0, s45, 0xc000
	ds_read_b128 v[158:161], v217
	ds_read_b128 v[170:173], v217 offset:1024
	ds_read_b128 v[174:177], v217 offset:2048
	ds_read_b128 v[178:181], v217 offset:3072
	ds_read_b128 v[182:185], v217 offset:4096
	ds_read_b128 v[186:189], v217 offset:5120
	ds_read_b128 v[190:193], v217 offset:6144
	ds_read_b128 v[194:197], v217 offset:7168
	global_load_lds_dwordx4 v[210:211], off
	v_lshl_add_u64 v[210:211], s[10:11], 0, v[206:207]
	s_add_i32 m0, s45, 0xe000
	s_nop 0
	global_load_lds_dwordx4 v[210:211], off
	s_waitcnt vmcnt(8)
	s_waitcnt lgkmcnt(0)
	s_barrier
	s_setprio 1
	s_waitcnt lgkmcnt(0)
	v_mfma_f32_16x16x32_bf16 v[166:169], v[86:89], v[158:161], v[166:169]
	v_mfma_f32_16x16x32_bf16 v[162:165], v[110:113], v[158:161], v[162:165]
	v_mfma_f32_16x16x32_bf16 v[130:133], v[86:89], v[174:177], v[130:133]
	v_mfma_f32_16x16x32_bf16 v[126:129], v[110:113], v[174:177], v[126:129]
	v_mfma_f32_16x16x32_bf16 v[106:109], v[86:89], v[182:185], v[106:109]
	v_mfma_f32_16x16x32_bf16 v[102:105], v[110:113], v[182:185], v[102:105]
	v_mfma_f32_16x16x32_bf16 v[82:85], v[86:89], v[190:193], v[82:85]
	v_mfma_f32_16x16x32_bf16 v[78:81], v[110:113], v[190:193], v[78:81]
	v_mfma_f32_16x16x32_bf16 v[166:169], v[98:101], v[170:173], v[166:169]
	v_mfma_f32_16x16x32_bf16 v[162:165], v[118:121], v[170:173], v[162:165]
	v_mfma_f32_16x16x32_bf16 v[130:133], v[98:101], v[178:181], v[130:133]
	v_mfma_f32_16x16x32_bf16 v[126:129], v[118:121], v[178:181], v[126:129]
	v_mfma_f32_16x16x32_bf16 v[106:109], v[98:101], v[186:189], v[106:109]
	v_mfma_f32_16x16x32_bf16 v[102:105], v[118:121], v[186:189], v[102:105]
	v_mfma_f32_16x16x32_bf16 v[82:85], v[98:101], v[194:197], v[82:85]
	v_mfma_f32_16x16x32_bf16 v[78:81], v[118:121], v[194:197], v[78:81]
	s_setprio 0
	s_setprio 1
	v_mfma_f32_16x16x32_bf16 v[146:149], v[134:137], v[158:161], v[146:149]
	v_mfma_f32_16x16x32_bf16 v[142:145], v[150:153], v[158:161], v[142:145]
	v_mfma_f32_16x16x32_bf16 v[122:125], v[134:137], v[174:177], v[122:125]
	v_mfma_f32_16x16x32_bf16 v[114:117], v[150:153], v[174:177], v[114:117]
	v_mfma_f32_16x16x32_bf16 v[94:97], v[134:137], v[182:185], v[94:97]
	v_mfma_f32_16x16x32_bf16 v[90:93], v[150:153], v[182:185], v[90:93]
	v_mfma_f32_16x16x32_bf16 v[74:77], v[134:137], v[190:193], v[74:77]
	v_mfma_f32_16x16x32_bf16 v[70:73], v[150:153], v[190:193], v[70:73]
	v_mfma_f32_16x16x32_bf16 v[146:149], v[138:141], v[170:173], v[146:149]
	v_mfma_f32_16x16x32_bf16 v[142:145], v[154:157], v[170:173], v[142:145]
	v_mfma_f32_16x16x32_bf16 v[122:125], v[138:141], v[178:181], v[122:125]
	v_mfma_f32_16x16x32_bf16 v[114:117], v[154:157], v[178:181], v[114:117]
	v_mfma_f32_16x16x32_bf16 v[94:97], v[138:141], v[186:189], v[94:97]
	v_mfma_f32_16x16x32_bf16 v[90:93], v[154:157], v[186:189], v[90:93]
	v_mfma_f32_16x16x32_bf16 v[74:77], v[138:141], v[194:197], v[74:77]
	v_mfma_f32_16x16x32_bf16 v[70:73], v[154:157], v[194:197], v[70:73]
	s_setprio 0
	s_barrier
	s_add_i32 s63, s63, s42
	v_lshl_add_u64 v[210:211], s[64:65], 0, v[200:201]
	s_mov_b32 m0, s63
	ds_read_b128 v[158:161], v217 offset:16384
	ds_read_b128 v[170:173], v217 offset:17408
	ds_read_b128 v[174:177], v217 offset:18432
	ds_read_b128 v[178:181], v217 offset:19456
	ds_read_b128 v[182:185], v217 offset:20480
	ds_read_b128 v[186:189], v217 offset:21504
	ds_read_b128 v[190:193], v217 offset:22528
	ds_read_b128 v[194:197], v217 offset:23552
	s_cmp_eq_u32 s38, s99
	s_cbranch_scc1 .Lmy_g2_s2_last
	global_load_lds_dwordx4 v[210:211], off
	s_add_i32 m0, s63, 0x2000
	v_lshl_add_u64 v[232:233], s[64:65], 0, v[204:205]
	s_add_u32 s64, s64, s18
	s_addc_u32 s65, s65, 0
	s_add_i32 s39, s39, s42
	global_load_lds_dwordx4 v[232:233], off
	v_lshl_add_u64 v[234:235], s[64:65], 0, v[200:201]
	s_mov_b32 m0, s39
	v_lshl_add_u64 v[236:237], s[64:65], 0, v[204:205]
	global_load_lds_dwordx4 v[234:235], off
	s_add_i32 m0, s39, 0x2000
	v_lshl_add_u64 v[238:239], s[36:37], 0, v[2:3]
	global_load_lds_dwordx4 v[236:237], off
	s_mov_b32 m0, s45
	v_lshl_add_u64 v[240:241], s[36:37], 0, v[202:203]
	global_load_lds_dwordx4 v[238:239], off
	s_mov_b32 m0, s46
	s_nop 0
	global_load_lds_dwordx4 v[240:241], off
	s_waitcnt vmcnt(8)
.Lmy_g2_s2_join:
	s_waitcnt lgkmcnt(0)
	s_barrier
	s_setprio 1
	s_waitcnt lgkmcnt(0)
	v_mfma_f32_16x16x32_bf16 v[66:69], v[86:89], v[158:161], v[66:69]
	v_mfma_f32_16x16x32_bf16 v[62:65], v[110:113], v[158:161], v[62:65]
	v_mfma_f32_16x16x32_bf16 v[50:53], v[86:89], v[174:177], v[50:53]
	v_mfma_f32_16x16x32_bf16 v[46:49], v[110:113], v[174:177], v[46:49]
	v_mfma_f32_16x16x32_bf16 v[34:37], v[86:89], v[182:185], v[34:37]
	v_mfma_f32_16x16x32_bf16 v[30:33], v[110:113], v[182:185], v[30:33]
	v_mfma_f32_16x16x32_bf16 v[18:21], v[86:89], v[190:193], v[18:21]
	v_mfma_f32_16x16x32_bf16 v[14:17], v[110:113], v[190:193], v[14:17]
	v_mfma_f32_16x16x32_bf16 v[66:69], v[98:101], v[170:173], v[66:69]
	v_mfma_f32_16x16x32_bf16 v[62:65], v[118:121], v[170:173], v[62:65]
	v_mfma_f32_16x16x32_bf16 v[50:53], v[98:101], v[178:181], v[50:53]
	v_mfma_f32_16x16x32_bf16 v[46:49], v[118:121], v[178:181], v[46:49]
	v_mfma_f32_16x16x32_bf16 v[34:37], v[98:101], v[186:189], v[34:37]
	v_mfma_f32_16x16x32_bf16 v[30:33], v[118:121], v[186:189], v[30:33]
	v_mfma_f32_16x16x32_bf16 v[18:21], v[98:101], v[194:197], v[18:21]
	v_mfma_f32_16x16x32_bf16 v[14:17], v[118:121], v[194:197], v[14:17]
	s_setprio 0
	s_setprio 1
	v_mfma_f32_16x16x32_bf16 v[58:61], v[134:137], v[158:161], v[58:61]
	v_mfma_f32_16x16x32_bf16 v[54:57], v[150:153], v[158:161], v[54:57]
	v_mfma_f32_16x16x32_bf16 v[42:45], v[134:137], v[174:177], v[42:45]
	v_mfma_f32_16x16x32_bf16 v[38:41], v[150:153], v[174:177], v[38:41]
	v_mfma_f32_16x16x32_bf16 v[26:29], v[134:137], v[182:185], v[26:29]
	v_mfma_f32_16x16x32_bf16 v[22:25], v[150:153], v[182:185], v[22:25]
	v_mfma_f32_16x16x32_bf16 v[10:13], v[134:137], v[190:193], v[10:13]
	v_mfma_f32_16x16x32_bf16 v[6:9], v[150:153], v[190:193], v[6:9]
	v_mfma_f32_16x16x32_bf16 v[58:61], v[138:141], v[170:173], v[58:61]
	v_mfma_f32_16x16x32_bf16 v[54:57], v[154:157], v[170:173], v[54:57]
	v_mfma_f32_16x16x32_bf16 v[42:45], v[138:141], v[178:181], v[42:45]
	v_mfma_f32_16x16x32_bf16 v[38:41], v[154:157], v[178:181], v[38:41]
	v_mfma_f32_16x16x32_bf16 v[26:29], v[138:141], v[186:189], v[26:29]
	v_mfma_f32_16x16x32_bf16 v[22:25], v[154:157], v[186:189], v[22:25]
	v_mfma_f32_16x16x32_bf16 v[10:13], v[138:141], v[194:197], v[10:13]
	v_mfma_f32_16x16x32_bf16 v[6:9], v[154:157], v[194:197], v[6:9]
	s_setprio 0
	s_barrier
	s_add_i32 s39, 0, 0x18000
	v_add_u32_e32 v0, s39, v213
	s_add_i32 s63, 0, 0x1c000
	ds_read_b128 v[86:89], v0
	ds_read_b128 v[98:101], v0 offset:1024
	ds_read_b128 v[110:113], v0 offset:2048
	ds_read_b128 v[118:121], v0 offset:3072
	v_add_u32_e32 v0, s63, v213
	ds_read_b128 v[134:137], v0
	ds_read_b128 v[138:141], v0 offset:1024
	ds_read_b128 v[150:153], v0 offset:2048
	ds_read_b128 v[154:157], v0 offset:3072
	s_add_u32 s36, s36, s18
	s_addc_u32 s37, s37, 0
	s_mov_b32 m0, s47
	v_lshl_add_u64 v[242:243], s[36:37], 0, v[2:3]
	ds_read_b128 v[158:161], v217 offset:32768
	ds_read_b128 v[170:173], v217 offset:33792
	ds_read_b128 v[174:177], v217 offset:34816
	ds_read_b128 v[178:181], v217 offset:35840
	ds_read_b128 v[182:185], v217 offset:36864
	ds_read_b128 v[186:189], v217 offset:37888
	ds_read_b128 v[190:193], v217 offset:38912
	ds_read_b128 v[194:197], v217 offset:39936
	s_cmp_eq_u32 s38, s99
	s_cbranch_scc1 .Lmy_g2_s3_last
	global_load_lds_dwordx4 v[242:243], off
	v_lshl_add_u64 v[242:243], s[36:37], 0, v[202:203]
	s_mov_b32 m0, s48
	s_nop 0
	global_load_lds_dwordx4 v[242:243], off
	s_waitcnt vmcnt(8)
.Lmy_g2_s3_join:
	s_waitcnt lgkmcnt(0)
	s_barrier
	s_setprio 1
	s_waitcnt lgkmcnt(0)
	v_mfma_f32_16x16x32_bf16 v[166:169], v[86:89], v[158:161], v[166:169]
	v_mfma_f32_16x16x32_bf16 v[162:165], v[110:113], v[158:161], v[162:165]
	v_mfma_f32_16x16x32_bf16 v[130:133], v[86:89], v[174:177], v[130:133]
	v_mfma_f32_16x16x32_bf16 v[126:129], v[110:113], v[174:177], v[126:129]
	v_mfma_f32_16x16x32_bf16 v[106:109], v[86:89], v[182:185], v[106:109]
	v_mfma_f32_16x16x32_bf16 v[102:105], v[110:113], v[182:185], v[102:105]
	v_mfma_f32_16x16x32_bf16 v[82:85], v[86:89], v[190:193], v[82:85]
	v_mfma_f32_16x16x32_bf16 v[78:81], v[110:113], v[190:193], v[78:81]
	v_mfma_f32_16x16x32_bf16 v[166:169], v[98:101], v[170:173], v[166:169]
	v_mfma_f32_16x16x32_bf16 v[162:165], v[118:121], v[170:173], v[162:165]
	v_mfma_f32_16x16x32_bf16 v[130:133], v[98:101], v[178:181], v[130:133]
	v_mfma_f32_16x16x32_bf16 v[126:129], v[118:121], v[178:181], v[126:129]
	v_mfma_f32_16x16x32_bf16 v[106:109], v[98:101], v[186:189], v[106:109]
	v_mfma_f32_16x16x32_bf16 v[102:105], v[118:121], v[186:189], v[102:105]
	v_mfma_f32_16x16x32_bf16 v[82:85], v[98:101], v[194:197], v[82:85]
	v_mfma_f32_16x16x32_bf16 v[78:81], v[118:121], v[194:197], v[78:81]
	s_setprio 0
	s_setprio 1
	v_mfma_f32_16x16x32_bf16 v[146:149], v[134:137], v[158:161], v[146:149]
	v_mfma_f32_16x16x32_bf16 v[142:145], v[150:153], v[158:161], v[142:145]
	v_mfma_f32_16x16x32_bf16 v[122:125], v[134:137], v[174:177], v[122:125]
	v_mfma_f32_16x16x32_bf16 v[114:117], v[150:153], v[174:177], v[114:117]
	v_mfma_f32_16x16x32_bf16 v[94:97], v[134:137], v[182:185], v[94:97]
	v_mfma_f32_16x16x32_bf16 v[90:93], v[150:153], v[182:185], v[90:93]
	v_mfma_f32_16x16x32_bf16 v[74:77], v[134:137], v[190:193], v[74:77]
	v_mfma_f32_16x16x32_bf16 v[70:73], v[150:153], v[190:193], v[70:73]
	v_mfma_f32_16x16x32_bf16 v[146:149], v[138:141], v[170:173], v[146:149]
	v_mfma_f32_16x16x32_bf16 v[142:145], v[154:157], v[170:173], v[142:145]
	v_mfma_f32_16x16x32_bf16 v[122:125], v[138:141], v[178:181], v[122:125]
	v_mfma_f32_16x16x32_bf16 v[114:117], v[154:157], v[178:181], v[114:117]
	v_mfma_f32_16x16x32_bf16 v[94:97], v[138:141], v[186:189], v[94:97]
	v_mfma_f32_16x16x32_bf16 v[90:93], v[154:157], v[186:189], v[90:93]
	v_mfma_f32_16x16x32_bf16 v[74:77], v[138:141], v[194:197], v[74:77]
	v_mfma_f32_16x16x32_bf16 v[70:73], v[154:157], v[194:197], v[70:73]
	s_setprio 0
	s_barrier
	s_add_i32 s36, s39, s42
	v_lshl_add_u64 v[210:211], v[210:211], 0, s[96:97]
	s_mov_b32 m0, s36
	ds_read_b128 v[158:161], v217 offset:49152
	ds_read_b128 v[170:173], v217 offset:50176
	ds_read_b128 v[174:177], v217 offset:51200
	ds_read_b128 v[178:181], v217 offset:52224
	ds_read_b128 v[182:185], v217 offset:53248
	ds_read_b128 v[186:189], v217 offset:54272
	ds_read_b128 v[190:193], v217 offset:55296
	ds_read_b128 v[194:197], v217 offset:56320
	s_cmp_eq_u32 s38, s99
	s_cbranch_scc1 .Lmy_g2_s4_last
	global_load_lds_dwordx4 v[210:211], off
	v_lshl_add_u64 v[210:211], v[232:233], 0, s[96:97]
	s_add_i32 m0, s36, 0x2000
	s_add_i32 s36, s63, s42
	global_load_lds_dwordx4 v[210:211], off
	v_lshl_add_u64 v[210:211], v[234:235], 0, s[96:97]
	s_mov_b32 m0, s36
	s_nop 0
	global_load_lds_dwordx4 v[210:211], off
	v_lshl_add_u64 v[210:211], v[236:237], 0, s[96:97]
	s_add_i32 m0, s36, 0x2000
	s_nop 0
	global_load_lds_dwordx4 v[210:211], off
	v_lshl_add_u64 v[210:211], v[238:239], 0, s[96:97]
	s_mov_b32 m0, s51
	s_nop 0
	global_load_lds_dwordx4 v[210:211], off
	v_lshl_add_u64 v[210:211], v[240:241], 0, s[96:97]
	s_mov_b32 m0, s52
	s_nop 0
	global_load_lds_dwordx4 v[210:211], off
	s_waitcnt vmcnt(8)
.Lmy_g2_s4_join:
	s_waitcnt lgkmcnt(0)
	s_barrier
	s_setprio 1
	s_waitcnt lgkmcnt(0)
	v_mfma_f32_16x16x32_bf16 v[66:69], v[86:89], v[158:161], v[66:69]
	v_mfma_f32_16x16x32_bf16 v[62:65], v[110:113], v[158:161], v[62:65]
	v_mfma_f32_16x16x32_bf16 v[50:53], v[86:89], v[174:177], v[50:53]
	v_mfma_f32_16x16x32_bf16 v[46:49], v[110:113], v[174:177], v[46:49]
	v_mfma_f32_16x16x32_bf16 v[34:37], v[86:89], v[182:185], v[34:37]
	v_mfma_f32_16x16x32_bf16 v[30:33], v[110:113], v[182:185], v[30:33]
	v_mfma_f32_16x16x32_bf16 v[18:21], v[86:89], v[190:193], v[18:21]
	v_mfma_f32_16x16x32_bf16 v[14:17], v[110:113], v[190:193], v[14:17]
	v_mfma_f32_16x16x32_bf16 v[66:69], v[98:101], v[170:173], v[66:69]
	v_mfma_f32_16x16x32_bf16 v[62:65], v[118:121], v[170:173], v[62:65]
	v_mfma_f32_16x16x32_bf16 v[50:53], v[98:101], v[178:181], v[50:53]
	v_mfma_f32_16x16x32_bf16 v[46:49], v[118:121], v[178:181], v[46:49]
	v_mfma_f32_16x16x32_bf16 v[34:37], v[98:101], v[186:189], v[34:37]
	v_mfma_f32_16x16x32_bf16 v[30:33], v[118:121], v[186:189], v[30:33]
	v_mfma_f32_16x16x32_bf16 v[18:21], v[98:101], v[194:197], v[18:21]
	v_mfma_f32_16x16x32_bf16 v[14:17], v[118:121], v[194:197], v[14:17]
	s_setprio 0
	s_setprio 1
	v_mfma_f32_16x16x32_bf16 v[58:61], v[134:137], v[158:161], v[58:61]
	v_mfma_f32_16x16x32_bf16 v[54:57], v[150:153], v[158:161], v[54:57]
	v_mfma_f32_16x16x32_bf16 v[42:45], v[134:137], v[174:177], v[42:45]
	v_mfma_f32_16x16x32_bf16 v[38:41], v[150:153], v[174:177], v[38:41]
	v_mfma_f32_16x16x32_bf16 v[26:29], v[134:137], v[182:185], v[26:29]
	v_mfma_f32_16x16x32_bf16 v[22:25], v[150:153], v[182:185], v[22:25]
	v_mfma_f32_16x16x32_bf16 v[10:13], v[134:137], v[190:193], v[10:13]
	v_mfma_f32_16x16x32_bf16 v[6:9], v[150:153], v[190:193], v[6:9]
	v_mfma_f32_16x16x32_bf16 v[58:61], v[138:141], v[170:173], v[58:61]
	v_mfma_f32_16x16x32_bf16 v[54:57], v[154:157], v[170:173], v[54:57]
	v_mfma_f32_16x16x32_bf16 v[42:45], v[138:141], v[178:181], v[42:45]
	v_mfma_f32_16x16x32_bf16 v[38:41], v[154:157], v[178:181], v[38:41]
	v_mfma_f32_16x16x32_bf16 v[26:29], v[138:141], v[186:189], v[26:29]
	v_mfma_f32_16x16x32_bf16 v[22:25], v[154:157], v[186:189], v[22:25]
	v_mfma_f32_16x16x32_bf16 v[10:13], v[138:141], v[194:197], v[10:13]
	v_mfma_f32_16x16x32_bf16 v[6:9], v[154:157], v[194:197], v[6:9]
	s_setprio 0
	s_barrier
	s_add_u32 s61, s61, 0x100
	s_addc_u32 s62, s62, 0
	s_add_u32 s10, s10, 0x100
	s_addc_u32 s11, s11, 0
	s_cmp_ge_u32 s38, s50
	s_mov_b32 s36, s38
	s_cbranch_scc0 .LBB0_320
	s_and_b64 vcc, exec, s[26:27]
	s_cbranch_vccz .LBB0_323
	s_barrier

.LBB0_653:
	s_lshl_b32 s4, s4, 5
	s_add_i32 m0, s45, 0x18000
	v_lshl_add_u64 v[6:7], v[6:7], 0, s[96:97]
	v_lshl_or_b32 v179, s5, 6, v5
	s_lshl_b32 s5, s5, 13
	v_lshlrev_b32_e32 v14, 2, v5
	s_and_b32 s34, s4, 0x60
	s_waitcnt vmcnt(2)
	s_barrier
	global_load_lds_dwordx4 v[6:7], off
	v_lshl_add_u64 v[6:7], v[8:9], 0, s[96:97]
	s_add_i32 m0, s45, 0x1a000
	s_add_i32 s75, s45, 0x8000
	s_add_i32 s76, s45, 0xa000
	v_lshl_or_b32 v0, v5, 6, v177
	v_and_b32_e32 v14, 32, v14
	global_load_lds_dwordx4 v[6:7], off
	v_lshl_add_u64 v[6:7], v[12:13], 0, s[96:97]
	s_mov_b32 m0, s75
	s_add_u32 s4, s46, 0x40080
	v_bitop3_b32 v0, v0, s5, v14 bitop3:0xde
	global_load_lds_dwordx4 v[6:7], off
	v_lshl_add_u64 v[6:7], v[10:11], 0, s[96:97]
	s_mov_b32 m0, s76
	s_addc_u32 s5, s47, 0
	global_load_lds_dwordx4 v[6:7], off
	s_add_i32 m0, s45, 0x1c000
	v_lshl_add_u64 v[6:7], s[4:5], 0, v[162:163]
	global_load_lds_dwordx4 v[6:7], off
	v_lshl_add_u64 v[6:7], s[4:5], 0, v[166:167]
	s_add_i32 m0, s45, 0x1e000
	s_cmpk_lt_u32 s30, 0x100
	global_load_lds_dwordx4 v[6:7], off
	s_waitcnt vmcnt(6)
	v_lshl_or_b32 v180, s34, 7, v178
	s_cselect_b64 s[30:31], -1, 0
	v_or_b32_e32 v181, s34, v176
	s_mov_b32 s77, 0
	v_add_u32_e32 v182, 0, v0
	s_barrier
	s_branch .LBB0_656
.Lmy_g3_s2_last:
	s_waitcnt vmcnt(2)
	s_branch .Lmy_g3_s2_join
.Lmy_g3_s3_last:
	s_waitcnt vmcnt(0)
	s_branch .Lmy_g3_s3_join
.Lmy_g3_s4_last:
	s_waitcnt vmcnt(0)
	s_branch .Lmy_g3_s4_join
.LBB0_654:
	s_mov_b64 s[42:43], 0

.LBB0_658:
	s_ashr_i32 s37, s36, 31
	s_lshl_b64 s[38:39], s[36:37], 19
	s_add_u32 s38, s26, s38
	s_addc_u32 s39, s27, s39
	s_and_b64 s[40:41], s[4:5], exec
	s_cselect_b32 s37, s39, s49
	s_cselect_b32 s43, s38, s48
	s_ashr_i32 s35, s34, 31
	s_lshl_b64 s[40:41], s[34:35], 19
	s_add_u32 s40, s18, s40
	s_addc_u32 s41, s19, s41
	s_and_b64 s[50:51], s[4:5], exec
	s_cselect_b32 s35, s41, s47
	s_cselect_b32 s78, s40, s46
	s_cselect_b32 s100, 0x7fff, 12
	s_add_u32 s79, s46, 0x100
	s_addc_u32 s80, s47, 0
	s_add_u32 s46, s48, 0x40080
	v_mov_b32_e32 v6, 0
	s_addc_u32 s47, s49, 0
	s_mov_b32 s81, -2
	v_mov_b32_e32 v7, v6
	v_mov_b32_e32 v8, v6
	v_mov_b32_e32 v9, v6
	v_mov_b32_e32 v10, v6
	v_mov_b32_e32 v11, v6
	v_mov_b32_e32 v12, v6
	v_mov_b32_e32 v13, v6
	v_mov_b32_e32 v22, v6
	v_mov_b32_e32 v23, v6
	v_mov_b32_e32 v24, v6
	s_waitcnt lgkmcnt(0)
	v_mov_b32_e32 v25, v6
	v_mov_b32_e32 v26, v6
	v_mov_b32_e32 v27, v6
	v_mov_b32_e32 v28, v6
	v_mov_b32_e32 v29, v6
	v_mov_b32_e32 v38, v6
	v_mov_b32_e32 v39, v6
	v_mov_b32_e32 v40, v6
	v_mov_b32_e32 v41, v6
	v_mov_b32_e32 v42, v6
	v_mov_b32_e32 v43, v6
	v_mov_b32_e32 v44, v6
	v_mov_b32_e32 v45, v6
	v_mov_b32_e32 v54, v6
	v_mov_b32_e32 v55, v6
	v_mov_b32_e32 v56, v6
	v_mov_b32_e32 v57, v6
	v_mov_b32_e32 v58, v6
	v_mov_b32_e32 v59, v6
	v_mov_b32_e32 v60, v6
	v_mov_b32_e32 v61, v6
	v_mov_b32_e32 v14, v6
	v_mov_b32_e32 v15, v6
	v_mov_b32_e32 v16, v6
	v_mov_b32_e32 v17, v6
	v_mov_b32_e32 v18, v6
	v_mov_b32_e32 v19, v6
	v_mov_b32_e32 v20, v6
	v_mov_b32_e32 v21, v6
	v_mov_b32_e32 v30, v6
	v_mov_b32_e32 v31, v6
	v_mov_b32_e32 v32, v6
	v_mov_b32_e32 v33, v6
	v_mov_b32_e32 v34, v6
	v_mov_b32_e32 v35, v6
	v_mov_b32_e32 v36, v6
	v_mov_b32_e32 v37, v6
	v_mov_b32_e32 v46, v6
	v_mov_b32_e32 v47, v6
	v_mov_b32_e32 v48, v6
	v_mov_b32_e32 v49, v6
	v_mov_b32_e32 v50, v6
	v_mov_b32_e32 v51, v6
	v_mov_b32_e32 v52, v6
	v_mov_b32_e32 v53, v6
	v_mov_b32_e32 v62, v6
	v_mov_b32_e32 v63, v6
	v_mov_b32_e32 v64, v6
	v_mov_b32_e32 v65, v6
	v_mov_b32_e32 v66, v6
	v_mov_b32_e32 v67, v6
	v_mov_b32_e32 v68, v6
	v_mov_b32_e32 v69, v6
	v_mov_b32_e32 v70, v6
	v_mov_b32_e32 v71, v6
	v_mov_b32_e32 v72, v6
	v_mov_b32_e32 v73, v6
	v_mov_b32_e32 v74, v6
	v_mov_b32_e32 v75, v6
	v_mov_b32_e32 v76, v6
	v_mov_b32_e32 v77, v6
	v_mov_b32_e32 v86, v6
	v_mov_b32_e32 v87, v6
	v_mov_b32_e32 v88, v6
	v_mov_b32_e32 v89, v6
	v_mov_b32_e32 v90, v6
	v_mov_b32_e32 v91, v6
	v_mov_b32_e32 v92, v6
	v_mov_b32_e32 v93, v6
	v_mov_b32_e32 v118, v6
	v_mov_b32_e32 v119, v6
	v_mov_b32_e32 v120, v6
	v_mov_b32_e32 v121, v6
	v_mov_b32_e32 v122, v6
	v_mov_b32_e32 v123, v6
	v_mov_b32_e32 v124, v6
	v_mov_b32_e32 v125, v6
	v_mov_b32_e32 v138, v6
	v_mov_b32_e32 v139, v6
	v_mov_b32_e32 v140, v6
	v_mov_b32_e32 v141, v6
	v_mov_b32_e32 v142, v6
	v_mov_b32_e32 v143, v6
	v_mov_b32_e32 v144, v6
	v_mov_b32_e32 v145, v6
	v_mov_b32_e32 v78, v6
	v_mov_b32_e32 v79, v6
	v_mov_b32_e32 v80, v6
	v_mov_b32_e32 v81, v6
	v_mov_b32_e32 v82, v6
	v_mov_b32_e32 v83, v6
	v_mov_b32_e32 v84, v6
	v_mov_b32_e32 v85, v6
	v_mov_b32_e32 v94, v6
	v_mov_b32_e32 v95, v6
	v_mov_b32_e32 v96, v6
	v_mov_b32_e32 v97, v6
	v_mov_b32_e32 v98, v6
	v_mov_b32_e32 v99, v6
	v_mov_b32_e32 v100, v6
	v_mov_b32_e32 v101, v6
	v_mov_b32_e32 v126, v6
	v_mov_b32_e32 v127, v6
	v_mov_b32_e32 v128, v6
	v_mov_b32_e32 v129, v6
	v_mov_b32_e32 v130, v6
	v_mov_b32_e32 v131, v6
	v_mov_b32_e32 v132, v6
	v_mov_b32_e32 v133, v6
	v_mov_b32_e32 v146, v6
	v_mov_b32_e32 v147, v6
	v_mov_b32_e32 v148, v6
	v_mov_b32_e32 v149, v6
	v_mov_b32_e32 v150, v6
	v_mov_b32_e32 v151, v6
	v_mov_b32_e32 v152, v6
	v_mov_b32_e32 v153, v6
.LBB0_659:
	s_add_u32 s48, s46, 0xfffc0080
	s_addc_u32 s49, s47, -1
	s_add_i32 s82, 0, 0x10000
	s_cmp_eq_u32 s81, 12
	s_cselect_b32 s51, s37, s49
	s_cselect_b32 s50, s43, s48
	v_add_u32_e32 v0, s82, v180
	s_cselect_b32 s49, s35, s80
	s_cselect_b32 s48, s78, s79
	s_add_i32 s84, 0, 0x14000
	ds_read_b128 v[102:105], v0
	ds_read_b128 v[106:109], v0 offset:1024
	ds_read_b128 v[110:113], v0 offset:2048
	ds_read_b128 v[114:117], v0 offset:3072
	v_add_u32_e32 v0, s84, v180
	ds_read_b128 v[134:137], v0
	ds_read_b128 v[154:157], v0 offset:1024
	ds_read_b128 v[158:161], v0 offset:2048
	ds_read_b128 v[184:187], v0 offset:3072
	v_lshl_add_u64 v[172:173], s[46:47], 0, v[170:171]
	s_add_i32 m0, s45, 0xc000
	ds_read_b128 v[188:191], v182
	ds_read_b128 v[192:195], v182 offset:1024
	ds_read_b128 v[200:203], v182 offset:2048
	ds_read_b128 v[204:207], v182 offset:3072
	ds_read_b128 v[208:211], v182 offset:4096
	ds_read_b128 v[212:215], v182 offset:5120
	ds_read_b128 v[232:235], v182 offset:6144
	ds_read_b128 v[236:239], v182 offset:7168
	global_load_lds_dwordx4 v[172:173], off
	v_lshl_add_u64 v[172:173], s[46:47], 0, v[168:169]
	s_add_i32 m0, s45, 0xe000
	s_nop 0
	global_load_lds_dwordx4 v[172:173], off
	s_waitcnt vmcnt(8)
	s_waitcnt lgkmcnt(0)
	s_barrier
	s_setprio 1
	s_waitcnt lgkmcnt(0)
	v_mfma_f32_16x16x32_bf16 v[150:153], v[102:105], v[188:191], v[150:153]
	v_mfma_f32_16x16x32_bf16 v[146:149], v[110:113], v[188:191], v[146:149]
	v_mfma_f32_16x16x32_bf16 v[130:133], v[102:105], v[200:203], v[130:133]
	v_mfma_f32_16x16x32_bf16 v[126:129], v[110:113], v[200:203], v[126:129]
	v_mfma_f32_16x16x32_bf16 v[98:101], v[102:105], v[208:211], v[98:101]
	v_mfma_f32_16x16x32_bf16 v[94:97], v[110:113], v[208:211], v[94:97]
	v_mfma_f32_16x16x32_bf16 v[82:85], v[102:105], v[232:235], v[82:85]
	v_mfma_f32_16x16x32_bf16 v[78:81], v[110:113], v[232:235], v[78:81]
	v_mfma_f32_16x16x32_bf16 v[150:153], v[106:109], v[192:195], v[150:153]
	v_mfma_f32_16x16x32_bf16 v[146:149], v[114:117], v[192:195], v[146:149]
	v_mfma_f32_16x16x32_bf16 v[130:133], v[106:109], v[204:207], v[130:133]
	v_mfma_f32_16x16x32_bf16 v[126:129], v[114:117], v[204:207], v[126:129]
	v_mfma_f32_16x16x32_bf16 v[98:101], v[106:109], v[212:215], v[98:101]
	v_mfma_f32_16x16x32_bf16 v[94:97], v[114:117], v[212:215], v[94:97]
	v_mfma_f32_16x16x32_bf16 v[82:85], v[106:109], v[236:239], v[82:85]
	v_mfma_f32_16x16x32_bf16 v[78:81], v[114:117], v[236:239], v[78:81]
	s_setprio 0
	s_setprio 1
	v_mfma_f32_16x16x32_bf16 v[142:145], v[134:137], v[188:191], v[142:145]
	v_mfma_f32_16x16x32_bf16 v[138:141], v[158:161], v[188:191], v[138:141]
	v_mfma_f32_16x16x32_bf16 v[122:125], v[134:137], v[200:203], v[122:125]
	v_mfma_f32_16x16x32_bf16 v[118:121], v[158:161], v[200:203], v[118:121]
	v_mfma_f32_16x16x32_bf16 v[90:93], v[134:137], v[208:211], v[90:93]
	v_mfma_f32_16x16x32_bf16 v[86:89], v[158:161], v[208:211], v[86:89]
	v_mfma_f32_16x16x32_bf16 v[74:77], v[134:137], v[232:235], v[74:77]
	v_mfma_f32_16x16x32_bf16 v[70:73], v[158:161], v[232:235], v[70:73]
	v_mfma_f32_16x16x32_bf16 v[142:145], v[154:157], v[192:195], v[142:145]
	v_mfma_f32_16x16x32_bf16 v[138:141], v[184:187], v[192:195], v[138:141]
	v_mfma_f32_16x16x32_bf16 v[122:125], v[154:157], v[204:207], v[122:125]
	v_mfma_f32_16x16x32_bf16 v[118:121], v[184:187], v[204:207], v[118:121]
	v_mfma_f32_16x16x32_bf16 v[90:93], v[154:157], v[212:215], v[90:93]
	v_mfma_f32_16x16x32_bf16 v[86:89], v[184:187], v[212:215], v[86:89]
	v_mfma_f32_16x16x32_bf16 v[74:77], v[154:157], v[236:239], v[74:77]
	v_mfma_f32_16x16x32_bf16 v[70:73], v[184:187], v[236:239], v[70:73]
	s_setprio 0
	s_barrier
	s_add_i32 s82, s82, s69
	v_lshl_add_u64 v[172:173], s[48:49], 0, v[162:163]
	s_mov_b32 m0, s82
	ds_read_b128 v[188:191], v182 offset:16384
	ds_read_b128 v[192:195], v182 offset:17408
	ds_read_b128 v[200:203], v182 offset:18432
	ds_read_b128 v[204:207], v182 offset:19456
	ds_read_b128 v[208:211], v182 offset:20480
	ds_read_b128 v[212:215], v182 offset:21504
	ds_read_b128 v[232:235], v182 offset:22528
	ds_read_b128 v[236:239], v182 offset:23552
	s_cmp_eq_u32 s81, s100
	s_cbranch_scc1 .Lmy_g3_s2_last
	global_load_lds_dwordx4 v[172:173], off
	s_add_i32 m0, s82, 0x2000
	s_add_u32 s82, s48, 0x40000
	v_lshl_add_u64 v[196:197], s[48:49], 0, v[166:167]
	s_addc_u32 s83, s49, 0
	s_add_i32 s84, s84, s69
	global_load_lds_dwordx4 v[196:197], off
	v_lshl_add_u64 v[216:217], s[82:83], 0, v[162:163]
	s_mov_b32 m0, s84
	v_lshl_add_u64 v[240:241], s[50:51], 0, v[164:165]
	global_load_lds_dwordx4 v[216:217], off
	v_lshl_add_u64 v[216:217], s[82:83], 0, v[166:167]
	s_add_i32 m0, s84, 0x2000
	s_nop 0
	global_load_lds_dwordx4 v[216:217], off
	v_lshl_add_u64 v[216:217], s[50:51], 0, v[2:3]
	s_mov_b32 m0, s45
	s_nop 0
	global_load_lds_dwordx4 v[216:217], off
	s_mov_b32 m0, s72
	s_nop 0
	global_load_lds_dwordx4 v[240:241], off
	s_waitcnt vmcnt(8)
.Lmy_g3_s2_join:
	s_waitcnt lgkmcnt(0)
	s_barrier
	s_setprio 1
	s_waitcnt lgkmcnt(0)
	v_mfma_f32_16x16x32_bf16 v[66:69], v[102:105], v[188:191], v[66:69]
	v_mfma_f32_16x16x32_bf16 v[62:65], v[110:113], v[188:191], v[62:65]
	v_mfma_f32_16x16x32_bf16 v[50:53], v[102:105], v[200:203], v[50:53]
	v_mfma_f32_16x16x32_bf16 v[46:49], v[110:113], v[200:203], v[46:49]
	v_mfma_f32_16x16x32_bf16 v[34:37], v[102:105], v[208:211], v[34:37]
	v_mfma_f32_16x16x32_bf16 v[30:33], v[110:113], v[208:211], v[30:33]
	v_mfma_f32_16x16x32_bf16 v[18:21], v[102:105], v[232:235], v[18:21]
	v_mfma_f32_16x16x32_bf16 v[14:17], v[110:113], v[232:235], v[14:17]
	v_mfma_f32_16x16x32_bf16 v[66:69], v[106:109], v[192:195], v[66:69]
	v_mfma_f32_16x16x32_bf16 v[62:65], v[114:117], v[192:195], v[62:65]
	v_mfma_f32_16x16x32_bf16 v[50:53], v[106:109], v[204:207], v[50:53]
	v_mfma_f32_16x16x32_bf16 v[46:49], v[114:117], v[204:207], v[46:49]
	v_mfma_f32_16x16x32_bf16 v[34:37], v[106:109], v[212:215], v[34:37]
	v_mfma_f32_16x16x32_bf16 v[30:33], v[114:117], v[212:215], v[30:33]
	v_mfma_f32_16x16x32_bf16 v[18:21], v[106:109], v[236:239], v[18:21]
	v_mfma_f32_16x16x32_bf16 v[14:17], v[114:117], v[236:239], v[14:17]
	s_setprio 0
	s_setprio 1
	v_mfma_f32_16x16x32_bf16 v[58:61], v[134:137], v[188:191], v[58:61]
	v_mfma_f32_16x16x32_bf16 v[54:57], v[158:161], v[188:191], v[54:57]
	v_mfma_f32_16x16x32_bf16 v[42:45], v[134:137], v[200:203], v[42:45]
	v_mfma_f32_16x16x32_bf16 v[38:41], v[158:161], v[200:203], v[38:41]
	v_mfma_f32_16x16x32_bf16 v[26:29], v[134:137], v[208:211], v[26:29]
	v_mfma_f32_16x16x32_bf16 v[22:25], v[158:161], v[208:211], v[22:25]
	v_mfma_f32_16x16x32_bf16 v[10:13], v[134:137], v[232:235], v[10:13]
	v_mfma_f32_16x16x32_bf16 v[6:9], v[158:161], v[232:235], v[6:9]
	v_mfma_f32_16x16x32_bf16 v[58:61], v[154:157], v[192:195], v[58:61]
	v_mfma_f32_16x16x32_bf16 v[54:57], v[184:187], v[192:195], v[54:57]
	v_mfma_f32_16x16x32_bf16 v[42:45], v[154:157], v[204:207], v[42:45]
	v_mfma_f32_16x16x32_bf16 v[38:41], v[184:187], v[204:207], v[38:41]
	v_mfma_f32_16x16x32_bf16 v[26:29], v[154:157], v[212:215], v[26:29]
	v_mfma_f32_16x16x32_bf16 v[22:25], v[184:187], v[212:215], v[22:25]
	v_mfma_f32_16x16x32_bf16 v[10:13], v[154:157], v[236:239], v[10:13]
	v_mfma_f32_16x16x32_bf16 v[6:9], v[184:187], v[236:239], v[6:9]
	s_setprio 0
	s_barrier
	s_add_i32 s82, 0, 0x18000
	v_add_u32_e32 v0, s82, v180
	s_add_i32 s83, 0, 0x1c000
	ds_read_b128 v[102:105], v0
	ds_read_b128 v[106:109], v0 offset:1024
	ds_read_b128 v[110:113], v0 offset:2048
	ds_read_b128 v[114:117], v0 offset:3072
	v_add_u32_e32 v0, s83, v180
	ds_read_b128 v[134:137], v0
	ds_read_b128 v[154:157], v0 offset:1024
	ds_read_b128 v[158:161], v0 offset:2048
	ds_read_b128 v[184:187], v0 offset:3072
	s_add_u32 s50, s50, 0x40000
	s_addc_u32 s51, s51, 0
	s_mov_b32 m0, s73
	v_lshl_add_u64 v[242:243], s[50:51], 0, v[2:3]
	ds_read_b128 v[188:191], v182 offset:32768
	ds_read_b128 v[192:195], v182 offset:33792
	ds_read_b128 v[200:203], v182 offset:34816
	ds_read_b128 v[204:207], v182 offset:35840
	ds_read_b128 v[208:211], v182 offset:36864
	ds_read_b128 v[212:215], v182 offset:37888
	ds_read_b128 v[232:235], v182 offset:38912
	ds_read_b128 v[236:239], v182 offset:39936
	s_cmp_eq_u32 s81, s100
	s_cbranch_scc1 .Lmy_g3_s3_last
	global_load_lds_dwordx4 v[242:243], off
	v_lshl_add_u64 v[242:243], s[50:51], 0, v[164:165]
	s_mov_b32 m0, s74
	s_nop 0
	global_load_lds_dwordx4 v[242:243], off
	s_waitcnt vmcnt(8)
.Lmy_g3_s3_join:
	s_waitcnt lgkmcnt(0)
	s_barrier
	s_setprio 1
	s_waitcnt lgkmcnt(0)
	v_mfma_f32_16x16x32_bf16 v[150:153], v[102:105], v[188:191], v[150:153]
	v_mfma_f32_16x16x32_bf16 v[146:149], v[110:113], v[188:191], v[146:149]
	v_mfma_f32_16x16x32_bf16 v[130:133], v[102:105], v[200:203], v[130:133]
	v_mfma_f32_16x16x32_bf16 v[126:129], v[110:113], v[200:203], v[126:129]
	v_mfma_f32_16x16x32_bf16 v[98:101], v[102:105], v[208:211], v[98:101]
	v_mfma_f32_16x16x32_bf16 v[94:97], v[110:113], v[208:211], v[94:97]
	v_mfma_f32_16x16x32_bf16 v[82:85], v[102:105], v[232:235], v[82:85]
	v_mfma_f32_16x16x32_bf16 v[78:81], v[110:113], v[232:235], v[78:81]
	v_mfma_f32_16x16x32_bf16 v[150:153], v[106:109], v[192:195], v[150:153]
	v_mfma_f32_16x16x32_bf16 v[146:149], v[114:117], v[192:195], v[146:149]
	v_mfma_f32_16x16x32_bf16 v[130:133], v[106:109], v[204:207], v[130:133]
	v_mfma_f32_16x16x32_bf16 v[126:129], v[114:117], v[204:207], v[126:129]
	v_mfma_f32_16x16x32_bf16 v[98:101], v[106:109], v[212:215], v[98:101]
	v_mfma_f32_16x16x32_bf16 v[94:97], v[114:117], v[212:215], v[94:97]
	v_mfma_f32_16x16x32_bf16 v[82:85], v[106:109], v[236:239], v[82:85]
	v_mfma_f32_16x16x32_bf16 v[78:81], v[114:117], v[236:239], v[78:81]
	s_setprio 0
	s_setprio 1
	v_mfma_f32_16x16x32_bf16 v[142:145], v[134:137], v[188:191], v[142:145]
	v_mfma_f32_16x16x32_bf16 v[138:141], v[158:161], v[188:191], v[138:141]
	v_mfma_f32_16x16x32_bf16 v[122:125], v[134:137], v[200:203], v[122:125]
	v_mfma_f32_16x16x32_bf16 v[118:121], v[158:161], v[200:203], v[118:121]
	v_mfma_f32_16x16x32_bf16 v[90:93], v[134:137], v[208:211], v[90:93]
	v_mfma_f32_16x16x32_bf16 v[86:89], v[158:161], v[208:211], v[86:89]
	v_mfma_f32_16x16x32_bf16 v[74:77], v[134:137], v[232:235], v[74:77]
	v_mfma_f32_16x16x32_bf16 v[70:73], v[158:161], v[232:235], v[70:73]
	v_mfma_f32_16x16x32_bf16 v[142:145], v[154:157], v[192:195], v[142:145]
	v_mfma_f32_16x16x32_bf16 v[138:141], v[184:187], v[192:195], v[138:141]
	v_mfma_f32_16x16x32_bf16 v[122:125], v[154:157], v[204:207], v[122:125]
	v_mfma_f32_16x16x32_bf16 v[118:121], v[184:187], v[204:207], v[118:121]
	v_mfma_f32_16x16x32_bf16 v[90:93], v[154:157], v[212:215], v[90:93]
	v_mfma_f32_16x16x32_bf16 v[86:89], v[184:187], v[212:215], v[86:89]
	v_mfma_f32_16x16x32_bf16 v[74:77], v[154:157], v[236:239], v[74:77]
	v_mfma_f32_16x16x32_bf16 v[70:73], v[184:187], v[236:239], v[70:73]
	s_setprio 0
	s_barrier
	s_add_i32 s50, s82, s69
	v_lshl_add_u64 v[172:173], v[172:173], 0, s[96:97]
	s_mov_b32 m0, s50
	ds_read_b128 v[188:191], v182 offset:49152
	ds_read_b128 v[192:195], v182 offset:50176
	ds_read_b128 v[200:203], v182 offset:51200
	ds_read_b128 v[204:207], v182 offset:52224
	ds_read_b128 v[208:211], v182 offset:53248
	ds_read_b128 v[212:215], v182 offset:54272
	ds_read_b128 v[232:235], v182 offset:55296
	ds_read_b128 v[236:239], v182 offset:56320
	s_cmp_eq_u32 s81, s100
	s_cbranch_scc1 .Lmy_g3_s4_last
	global_load_lds_dwordx4 v[172:173], off
	s_add_i32 m0, s50, 0x2000
	s_add_u32 s48, s48, 0x40080
	v_lshl_add_u64 v[172:173], v[196:197], 0, s[96:97]
	s_addc_u32 s49, s49, 0
	s_add_i32 s50, s83, s69
	global_load_lds_dwordx4 v[172:173], off
	v_lshl_add_u64 v[172:173], s[48:49], 0, v[162:163]
	s_mov_b32 m0, s50
	s_nop 0
	global_load_lds_dwordx4 v[172:173], off
	v_lshl_add_u64 v[172:173], s[48:49], 0, v[166:167]
	s_add_i32 m0, s50, 0x2000
	s_nop 0
	global_load_lds_dwordx4 v[172:173], off
	v_lshl_add_u64 v[172:173], v[216:217], 0, s[96:97]
	s_mov_b32 m0, s75
	s_nop 0
	global_load_lds_dwordx4 v[172:173], off
	v_lshl_add_u64 v[172:173], v[240:241], 0, s[96:97]
	s_mov_b32 m0, s76
	s_nop 0
	global_load_lds_dwordx4 v[172:173], off
	s_waitcnt vmcnt(8)
.Lmy_g3_s4_join:
	s_waitcnt lgkmcnt(0)
	s_barrier
	s_setprio 1
	s_waitcnt lgkmcnt(0)
	v_mfma_f32_16x16x32_bf16 v[66:69], v[102:105], v[188:191], v[66:69]
	v_mfma_f32_16x16x32_bf16 v[62:65], v[110:113], v[188:191], v[62:65]
	v_mfma_f32_16x16x32_bf16 v[50:53], v[102:105], v[200:203], v[50:53]
	v_mfma_f32_16x16x32_bf16 v[46:49], v[110:113], v[200:203], v[46:49]
	v_mfma_f32_16x16x32_bf16 v[34:37], v[102:105], v[208:211], v[34:37]
	v_mfma_f32_16x16x32_bf16 v[30:33], v[110:113], v[208:211], v[30:33]
	v_mfma_f32_16x16x32_bf16 v[18:21], v[102:105], v[232:235], v[18:21]
	v_mfma_f32_16x16x32_bf16 v[14:17], v[110:113], v[232:235], v[14:17]
	v_mfma_f32_16x16x32_bf16 v[66:69], v[106:109], v[192:195], v[66:69]
	v_mfma_f32_16x16x32_bf16 v[62:65], v[114:117], v[192:195], v[62:65]
	v_mfma_f32_16x16x32_bf16 v[50:53], v[106:109], v[204:207], v[50:53]
	v_mfma_f32_16x16x32_bf16 v[46:49], v[114:117], v[204:207], v[46:49]
	v_mfma_f32_16x16x32_bf16 v[34:37], v[106:109], v[212:215], v[34:37]
	v_mfma_f32_16x16x32_bf16 v[30:33], v[114:117], v[212:215], v[30:33]
	v_mfma_f32_16x16x32_bf16 v[18:21], v[106:109], v[236:239], v[18:21]
	v_mfma_f32_16x16x32_bf16 v[14:17], v[114:117], v[236:239], v[14:17]
	s_setprio 0
	s_setprio 1
	v_mfma_f32_16x16x32_bf16 v[58:61], v[134:137], v[188:191], v[58:61]
	v_mfma_f32_16x16x32_bf16 v[54:57], v[158:161], v[188:191], v[54:57]
	v_mfma_f32_16x16x32_bf16 v[42:45], v[134:137], v[200:203], v[42:45]
	v_mfma_f32_16x16x32_bf16 v[38:41], v[158:161], v[200:203], v[38:41]
	v_mfma_f32_16x16x32_bf16 v[26:29], v[134:137], v[208:211], v[26:29]
	v_mfma_f32_16x16x32_bf16 v[22:25], v[158:161], v[208:211], v[22:25]
	v_mfma_f32_16x16x32_bf16 v[10:13], v[134:137], v[232:235], v[10:13]
	v_mfma_f32_16x16x32_bf16 v[6:9], v[158:161], v[232:235], v[6:9]
	v_mfma_f32_16x16x32_bf16 v[58:61], v[154:157], v[192:195], v[58:61]
	v_mfma_f32_16x16x32_bf16 v[54:57], v[184:187], v[192:195], v[54:57]
	v_mfma_f32_16x16x32_bf16 v[42:45], v[154:157], v[204:207], v[42:45]
	v_mfma_f32_16x16x32_bf16 v[38:41], v[184:187], v[204:207], v[38:41]
	v_mfma_f32_16x16x32_bf16 v[26:29], v[154:157], v[212:215], v[26:29]
	v_mfma_f32_16x16x32_bf16 v[22:25], v[184:187], v[212:215], v[22:25]
	v_mfma_f32_16x16x32_bf16 v[10:13], v[154:157], v[236:239], v[10:13]
	v_mfma_f32_16x16x32_bf16 v[6:9], v[184:187], v[236:239], v[6:9]
	s_setprio 0
	s_barrier
	s_add_i32 s81, s81, 2
	s_add_u32 s79, s79, 0x100
	s_addc_u32 s80, s80, 0
	s_add_u32 s46, s46, 0x100
	s_addc_u32 s47, s47, 0
	s_cmp_gt_u32 s81, 13
	s_cbranch_scc0 .LBB0_659
	s_and_b64 vcc, exec, s[30:31]
	s_cbranch_vccz .LBB0_662
	s_barrier
